# attention item prologue: 4 Q loads + first K/V tile loads issued together (1 latency instead of 5)
# speedup vs baseline: 1.0050x; 1.0050x over previous
.LBB0_397:
	s_and_b32 s45, s0, 15
	s_ashr_i32 s37, s36, 31
	s_mul_i32 s3, s36, 0x1800
	s_mul_hi_i32 s1, s36, 0x1800
	s_add_u32 s3, s78, s3
	v_readlane_b32 s2, v252, 50
	s_addc_u32 s1, s2, s1
	s_lshl_b32 s5, s45, 7
	s_add_u32 s30, s3, s5
	s_addc_u32 s31, s1, 0
	v_readlane_b32 s2, v250, 19
	v_readlane_b32 s3, v250, 20
	s_add_u32 s28, s2, s5
	v_mov_b32_e32 v6, v168
	s_addc_u32 s29, s3, 0
	s_lshl_b32 s0, s0, 7
	s_and_b32 s0, s0, 0x700
	v_ashrrev_i32_e32 v0, 6, v6
	v_and_b32_e32 v62, 63, v6
	v_and_b32_e32 v1, 0x3fffffc0, v6
	v_and_b32_e32 v200, 31, v6
	v_lshl_add_u32 v175, v1, 2, v192
	v_lshl_add_u32 v1, v0, 12, v192
	v_lshlrev_b32_e32 v7, 4, v62
	v_lshlrev_b32_e32 v174, 5, v0
	s_add_u32 s39, s73, s0
	v_bfe_u32 v201, v6, 5, 1
	v_add_u32_e32 v204, v1, v7
	v_or_b32_e32 v2, v174, v200
	v_mov_b64_e32 v[0:1], s[30:31]
	s_movk_i32 s0, 0x1800
	v_mad_i64_i32 v[0:1], s[0:1], v2, s0, v[0:1]
	v_lshlrev_b32_e32 v176, 4, v201
	v_mov_b32_e32 v177, v171
	v_lshl_add_u64 v[4:5], v[0:1], 0, v[176:177]
	global_load_dwordx4 v[28:31], v[4:5], off
	global_load_dwordx4 v[16:19], v[4:5], off offset:32
	global_load_dwordx4 v[20:23], v[4:5], off offset:64
	global_load_dwordx4 v[24:27], v[4:5], off offset:96
	v_lshlrev_b32_e32 v12, 3, v6
	s_movk_i32 s1, 0xe0
	s_mov_b32 s0, 0x7ffffc
	s_addc_u32 s42, s63, 0
	s_cmp_lg_u32 0x100, -1
	s_mul_i32 s44, s38, 0x1800
	s_mul_hi_i32 s43, s38, 0x1800
	v_and_b32_e32 v8, 0x70, v6
	v_lshlrev_b32_e32 v72, 7, v200
	v_and_b32_e32 v73, 0x70, v12
	v_or_b32_e32 v64, 32, v176
	v_bitop3_b32 v64, v64, v72, v73 bitop3:0xde
	v_add_u32_e32 v209, 0x100, v64
	s_mov_b32 s5, s4
	s_mov_b32 s10, s4
	s_mov_b32 s11, s4
	s_mov_b32 s12, s4
	s_mov_b32 s13, s4
	s_mov_b32 s14, s4
	s_mov_b32 s15, s4
	s_mov_b32 s16, s4
	s_mov_b32 s17, s4
	s_mov_b32 s18, s4
	s_mov_b32 s19, s4
	v_mov_b32_e32 v61, v171
	v_cmp_gt_u32_e64 s[40:41], 32, v62
	s_mov_b32 s50, 4
	s_movk_i32 s51, 0xc0
	v_lshl_add_u32 v177, v200, 2, v175
	v_mov_b32_e32 v178, 0
	v_and_b32_e32 v5, 24, v12
	v_ashrrev_i32_e32 v0, 4, v6
	v_lshlrev_b32_e32 v4, 5, v0
	v_lshrrev_b32_e32 v2, 5, v6
	v_bfe_u32 v3, v12, 5, 2
	v_and_or_b32 v4, v4, s1, v5
	v_and_or_b32 v2, v2, s0, v3
	v_lshlrev_b32_e32 v4, 1, v4
	v_lshl_or_b32 v13, v2, 9, v4
	v_add_u32_e32 v2, 32, v0
	v_lshrrev_b32_e32 v2, 1, v2
	v_and_or_b32 v2, v2, s0, v3
	s_movk_i32 s0, 0xc00
	v_and_b32_e32 v1, 0x78, v12
	v_mul_lo_u32 v0, v0, s0
	v_lshl_or_b32 v14, v2, 9, v4
	v_ashrrev_i32_e32 v2, 3, v6
	v_or_b32_e32 v0, v0, v1
	v_and_b32_e32 v3, 56, v12
	v_lshlrev_b32_e32 v170, 1, v0
	v_mul_lo_u32 v0, v2, s0
	v_or_b32_e32 v0, v0, v3
	s_cselect_b32 s0, 0x100, 0
	s_add_u32 s6, s39, s44
	v_lshlrev_b32_e32 v4, 7, v2
	v_lshlrev_b32_e32 v5, 1, v3
	v_lshlrev_b32_e32 v60, 1, v0
	v_lshlrev_b32_e32 v0, 3, v62
	v_and_b32_e32 v1, 0xc0, v7
	v_lshlrev_b32_e32 v2, 1, v6
	s_addc_u32 s7, s42, s43
	v_bitop3_b32 v15, v5, v4, v8 bitop3:0xde
	v_and_or_b32 v1, v0, 24, v1
	v_and_b32_e32 v2, 32, v2
	v_and_b32_e32 v0, 0x100, v0
	v_lshl_add_u64 v[4:5], s[6:7], 0, v[170:171]
	v_or3_b32 v63, v1, v2, v0
	s_add_u32 s8, s28, s44
	global_load_dwordx4 v[0:3], v170, s[6:7]
	v_add_co_u32_e32 v4, vcc, s33, v4
	s_addc_u32 s9, s29, s43
	s_nop 0
	v_addc_co_u32_e32 v5, vcc, 0, v5, vcc
	global_load_dwordx4 v[4:7], v[4:5], off
	v_add_u32_e32 v205, 0x100, v13
	global_load_dwordx4 v[8:11], v60, s[8:9]
	s_waitcnt vmcnt(3)
	ds_write_b128 v204, v[28:31] offset:51200
	ds_write_b128 v204, v[16:19] offset:52224
	ds_write_b128 v204, v[20:23] offset:53248
	ds_write_b128 v204, v[24:27] offset:54272
	s_waitcnt vmcnt(0)
	v_add_u32_e32 v206, 0x100, v14
	v_add_u32_e32 v207, 0x100, v15
	s_mov_b32 s6, s4
	s_mov_b32 s7, s4
	s_mov_b32 s8, s4
	s_mov_b32 s9, s4
	s_add_i32 s1, s38, 64
	v_add_u32_e32 v203, s0, v63
	v_lshl_add_u64 v[180:181], s[28:29], 0, v[60:61]
	s_waitcnt vmcnt(2)
	ds_write_b128 v205, v[0:3]
	v_bitop3_b32 v0, v176, v72, v73 bitop3:0xde
	v_add_u32_e32 v208, 0x100, v0
	s_waitcnt vmcnt(1)
	ds_write_b128 v206, v[4:7]
	s_waitcnt vmcnt(0)
	ds_write_b128 v207, v[8:11] offset:32768
	s_waitcnt lgkmcnt(0)
	s_barrier
	ds_read_b128 v[56:59], v204 offset:52224
	ds_read_b128 v[52:55], v204 offset:53248
	ds_read_b128 v[48:51], v204 offset:54272
	ds_read_b128 v[16:19], v208 offset:36864
	ds_read_b128 v[20:23], v208 offset:32768
	ds_read_b128 v[24:27], v204 offset:51200
	s_waitcnt lgkmcnt(0)
	v_mfma_f32_32x32x16_bf16 v[32:47], v[20:23], v[24:27], 0
	ds_read_b128 v[64:67], v209 offset:36864
	ds_read_b128 v[68:71], v209 offset:32768
	v_mov_b64_e32 v[0:1], s[4:5]
	v_mov_b64_e32 v[2:3], s[6:7]
	v_mov_b64_e32 v[4:5], s[8:9]
	v_mov_b64_e32 v[6:7], s[10:11]
	v_mov_b64_e32 v[8:9], s[12:13]
	v_mov_b64_e32 v[10:11], s[14:15]
	v_mfma_f32_32x32x16_bf16 v[16:31], v[16:19], v[24:27], 0
	v_mov_b64_e32 v[12:13], s[16:17]
	v_mov_b64_e32 v[14:15], s[18:19]
	s_add_i32 s12, s44, 0x60000
	s_mul_hi_i32 s5, s1, 0x1800
	s_add_u32 s6, s39, s12
	s_addc_u32 s7, s42, s5
	s_add_u32 s8, s28, s12
	s_waitcnt lgkmcnt(0)
	v_mfma_f32_32x32x16_bf16 v[32:47], v[68:71], v[56:59], v[32:47]
	s_addc_u32 s9, s29, s5
	s_add_i32 s1, s38, 0x80
	s_add_i32 s47, s44, 0xc0000
	s_mul_hi_i32 s46, s1, 0x1800
	v_mfma_f32_32x32x16_bf16 v[16:31], v[64:67], v[56:59], v[16:31]
	v_or_b32_e32 v56, 64, v176
	v_bitop3_b32 v56, v56, v72, v73 bitop3:0xde
	v_add_u32_e32 v210, 0x100, v56
	ds_read_b128 v[56:59], v210 offset:36864
	ds_read_b128 v[64:67], v210 offset:32768
	s_waitcnt lgkmcnt(0)
	v_mfma_f32_32x32x16_bf16 v[32:47], v[64:67], v[52:55], v[32:47]
	v_mfma_f32_32x32x16_bf16 v[16:31], v[56:59], v[52:55], v[16:31]
	v_or_b32_e32 v52, 0x60, v176
	v_bitop3_b32 v52, v52, v72, v73 bitop3:0xde
	v_add_u32_e32 v211, 0x100, v52
	ds_read_b128 v[52:55], v211 offset:36864
	ds_read_b128 v[56:59], v211 offset:32768
	s_waitcnt lgkmcnt(0)
	v_mfma_f32_32x32x16_bf16 v[32:47], v[56:59], v[48:51], v[32:47]
	v_mfma_f32_32x32x16_bf16 v[16:31], v[52:55], v[48:51], v[16:31]
	s_nop 10
	v_max_f32_e32 v48, v33, v33
	v_max_f32_e32 v49, v32, v32
	v_max_f32_e32 v48, v49, v48
	v_max3_f32 v48, v48, v34, v35
	v_max3_f32 v48, v48, v36, v37
	v_max3_f32 v48, v48, v38, v39
	v_max3_f32 v48, v48, v40, v41
	v_max3_f32 v48, v48, v42, v43
	v_max3_f32 v48, v48, v44, v45
	v_max3_f32 v48, v48, v46, v47
	v_max3_f32 v48, v48, v16, v17
	v_max3_f32 v48, v48, v18, v19
	v_max3_f32 v48, v48, v20, v21
	v_max3_f32 v48, v48, v22, v23
	v_max3_f32 v48, v48, v24, v25
	v_max3_f32 v48, v48, v26, v27
	v_max3_f32 v48, v48, v28, v29
	v_max3_f32 v48, v48, v30, v31
	v_mov_b32_e32 v49, v48
	s_nop 1
	v_permlane32_swap_b32_e32 v48, v49
	v_max_f32_e32 v49, v49, v49
	v_max_f32_e32 v48, v48, v48
	v_max_f32_e32 v48, v48, v49
	v_sub_f32_e32 v36, v36, v48
	v_sub_f32_e32 v37, v37, v48
	v_exp_f32_e32 v53, v36
	v_exp_f32_e32 v54, v37
	v_lshl_add_u64 v[36:37], s[6:7], 0, v[170:171]
	v_add_co_u32_e32 v36, vcc, s33, v36
	v_sub_f32_e32 v32, v32, v48
	v_sub_f32_e32 v33, v33, v48
	v_sub_f32_e32 v34, v34, v48
	v_sub_f32_e32 v35, v35, v48
	v_sub_f32_e32 v38, v38, v48
	v_sub_f32_e32 v39, v39, v48
	v_sub_f32_e32 v40, v40, v48
	v_sub_f32_e32 v41, v41, v48
	v_sub_f32_e32 v42, v42, v48
	v_sub_f32_e32 v43, v43, v48
	v_sub_f32_e32 v44, v44, v48
	v_sub_f32_e32 v45, v45, v48
	v_sub_f32_e32 v46, v46, v48
	v_sub_f32_e32 v47, v47, v48
	v_addc_co_u32_e32 v37, vcc, 0, v37, vcc
	v_exp_f32_e32 v49, v32
	v_exp_f32_e32 v50, v33
	v_exp_f32_e32 v51, v34
	v_exp_f32_e32 v52, v35
	v_exp_f32_e32 v55, v38
	v_exp_f32_e32 v56, v39
	v_exp_f32_e32 v57, v40
	v_exp_f32_e32 v58, v41
	v_exp_f32_e32 v59, v42
	v_exp_f32_e32 v64, v43
	v_exp_f32_e32 v65, v44
	v_exp_f32_e32 v66, v45
	v_exp_f32_e32 v46, v46
	v_exp_f32_e32 v47, v47
	v_cvt_pk_bf16_f32 v144, v49, v50
	v_cvt_pk_bf16_f32 v145, v51, v52
	v_cvt_pk_bf16_f32 v146, v53, v54
	v_cvt_pk_bf16_f32 v147, v55, v56
	v_cvt_pk_bf16_f32 v140, v57, v58
	v_cvt_pk_bf16_f32 v141, v59, v64
	v_cvt_pk_bf16_f32 v142, v65, v66
	v_cvt_pk_bf16_f32 v143, v46, v47
	global_load_dwordx4 v[32:35], v170, s[6:7]
	s_nop 0
	global_load_dwordx4 v[36:39], v[36:37], off
	s_nop 0
	global_load_dwordx4 v[40:43], v60, s[8:9]
	s_add_u32 s6, s28, s47
	s_addc_u32 s7, s29, s46
	global_load_dwordx4 v[128:131], v60, s[6:7]
	s_add_u32 s6, s39, s47
	s_addc_u32 s7, s42, s46
	v_lshl_add_u64 v[44:45], s[6:7], 0, v[170:171]
	v_add_co_u32_e32 v44, vcc, s33, v44
	v_add_f32_e32 v212, 0, v48
	s_nop 0
	v_addc_co_u32_e32 v45, vcc, 0, v45, vcc
	global_load_dwordx4 v[136:139], v[44:45], off
	global_load_dwordx4 v[132:135], v170, s[6:7]
	s_waitcnt vmcnt(3)
	s_waitcnt vmcnt(5)
	ds_write_b128 v205, v[32:35] offset:16384
	s_waitcnt vmcnt(4)
	ds_write_b128 v206, v[36:39] offset:16384
	s_waitcnt vmcnt(3)
	ds_write_b128 v207, v[40:43] offset:40960
	v_add_f32_e32 v32, 0, v49
	v_add_f32_e32 v32, v50, v32
	v_add_f32_e32 v32, v51, v32
	v_add_f32_e32 v32, v52, v32
	v_add_f32_e32 v32, v53, v32
	v_add_f32_e32 v32, v54, v32
	v_add_f32_e32 v32, v55, v32
	v_add_f32_e32 v32, v56, v32
	v_add_f32_e32 v32, v57, v32
	v_add_f32_e32 v32, v58, v32
	v_add_f32_e32 v32, v59, v32
	v_add_f32_e32 v32, v64, v32
	v_add_f32_e32 v32, v65, v32
	v_add_f32_e32 v32, v66, v32
	v_add_f32_e32 v32, v46, v32
	s_addk_i32 s0, 0x4000
	v_xor_b32_e32 v96, 0x80000000, v212
	v_add_f32_e32 v164, v47, v32
	v_sub_f32_e32 v95, v31, v48
	v_sub_f32_e32 v94, v30, v48
	v_sub_f32_e32 v93, v29, v48
	v_sub_f32_e32 v92, v28, v48
	v_sub_f32_e32 v91, v27, v48
	v_sub_f32_e32 v90, v26, v48
	v_sub_f32_e32 v89, v25, v48
	v_sub_f32_e32 v88, v24, v48
	v_sub_f32_e32 v87, v23, v48
	v_sub_f32_e32 v86, v22, v48
	v_sub_f32_e32 v85, v21, v48
	v_sub_f32_e32 v84, v20, v48
	v_sub_f32_e32 v83, v19, v48
	v_sub_f32_e32 v82, v18, v48
	v_sub_f32_e32 v81, v17, v48
	v_sub_f32_e32 v80, v16, v48
	v_add_u32_e32 v202, s0, v63
	v_mov_b64_e32 v[62:63], v[14:15]
	v_mov_b64_e32 v[46:47], v[14:15]
	v_mov_b64_e32 v[30:31], v[14:15]
	s_mov_b64 s[8:9], 0
	v_mov_b64_e32 v[60:61], v[12:13]
	v_mov_b64_e32 v[58:59], v[10:11]
	v_mov_b64_e32 v[56:57], v[8:9]
	v_mov_b64_e32 v[54:55], v[6:7]
	v_mov_b64_e32 v[52:53], v[4:5]
	v_mov_b64_e32 v[50:51], v[2:3]
	v_mov_b64_e32 v[48:49], v[0:1]
	v_mov_b64_e32 v[44:45], v[12:13]
	v_mov_b64_e32 v[42:43], v[10:11]
	v_mov_b64_e32 v[40:41], v[8:9]
	v_mov_b64_e32 v[38:39], v[6:7]
	v_mov_b64_e32 v[36:37], v[4:5]
	v_mov_b64_e32 v[34:35], v[2:3]
	v_mov_b64_e32 v[32:33], v[0:1]
	v_mov_b64_e32 v[28:29], v[12:13]
	v_mov_b64_e32 v[26:27], v[10:11]
	v_mov_b64_e32 v[24:25], v[8:9]
	v_mov_b64_e32 v[22:23], v[6:7]
	v_mov_b64_e32 v[20:21], v[4:5]
	v_mov_b64_e32 v[18:19], v[2:3]
	v_mov_b64_e32 v[16:17], v[0:1]
	v_mov_b32_e32 v97, v96
	v_mov_b32_e32 v98, v96
	v_mov_b32_e32 v99, v96
	v_mov_b32_e32 v100, v96
	v_mov_b32_e32 v101, v96
	v_mov_b32_e32 v102, v96
	v_mov_b32_e32 v103, v96
	v_mov_b32_e32 v104, v96
	v_mov_b32_e32 v105, v96
	v_mov_b32_e32 v106, v96
	v_mov_b32_e32 v107, v96
	v_mov_b32_e32 v108, v96
	v_mov_b32_e32 v109, v96
	v_mov_b32_e32 v110, v96
	v_mov_b32_e32 v111, v96
	s_waitcnt lgkmcnt(0)
	s_barrier
	s_mov_b32 s100, 0x14800
	s_mov_b32 s101, 0x18010
	v_add_u32_e32 v205, s100, v205
	v_add_u32_e32 v206, s100, v206
	v_add_u32_e32 v207, s101, v207
